# LDS-DMA loader wave at s_setprio 3 (it shares a SIMD with a prio-2 recurrence wave)
# speedup vs baseline: 1.0076x; 1.0076x over previous
; #define LAS __attribute__((address_space(3)))
; __device__ __forceinline__ void scan_prompt_wave(const Params& P, unsigned char* lds, int b, int h, int quarter) {
;     ...
;     if (wave == 4) {
;         const float* g0 = (const float*)(P.ws + WS_RSB) + ((size_t)(b * SEQ) * RH + h) * RSB_BLK;
;         LAS unsigned char* l3 = (LAS unsigned char*)lds;
;         int soff[SC_NP64];
; #pragma unroll
;         for (int j = 0; j < SC_NP64; ++j) { const int i = j * 64 + lane; const int ii = i < SC_NPIECE ? i : SC_NPIECE - 1; soff[j] = (ii / 97) * PST + (ii % 97) * 4; }
.LBB0_1235:
	s_setprio 3
	s_nop 0
	v_or_b32_e32 v3, 64, v1
	s_movk_i32 s2, 0x60
	v_lshlrev_b16_e32 v4, 2, v3
	v_cmp_lt_u16_e32 vcc, s2, v3
	v_or_b32_e32 v3, 0xc0, v1
	v_mul_lo_u16_e32 v6, 0xa9, v3
	v_lshlrev_b16_e32 v7, 2, v3
	v_or_b32_e32 v3, 0x100, v1
	s_movk_i32 s2, 0x2a4
	v_mul_u32_u24_sdwa v8, v3, s2 dst_sel:DWORD dst_unused:UNUSED_PAD src0_sel:WORD_0 src1_sel:DWORD
	v_lshlrev_b16_e32 v9, 2, v3
	v_or_b32_e32 v3, 0x140, v1
	v_mul_u32_u24_sdwa v10, v3, s2 dst_sel:DWORD dst_unused:UNUSED_PAD src0_sel:WORD_0 src1_sel:DWORD
	s_movk_i32 s4, 0x61
	v_mul_lo_u16_sdwa v10, v10, s4 dst_sel:DWORD dst_unused:UNUSED_PAD src0_sel:WORD_1 src1_sel:DWORD
	v_sub_u16_e32 v11, v3, v10
	v_or_b32_e32 v3, 0x180, v1
	s_movk_i32 s3, 0x794
	v_mul_u32_u24_sdwa v10, v3, s2 dst_sel:DWORD dst_unused:UNUSED_PAD src0_sel:WORD_0 src1_sel:DWORD
	s_waitcnt lgkmcnt(6)
	v_lshlrev_b16_e32 v13, 2, v3
	v_or_b32_e32 v3, 0x1c0, v1
	v_mul_lo_u16_sdwa v15, v10, s3 dst_sel:DWORD dst_unused:UNUSED_PAD src0_sel:WORD_1 src1_sel:DWORD
	v_mul_u32_u24_sdwa v10, v3, s2 dst_sel:DWORD dst_unused:UNUSED_PAD src0_sel:WORD_0 src1_sel:DWORD
	v_lshlrev_b16_e32 v17, 2, v3
	v_or_b32_e32 v3, 0x200, v1
	v_mul_lo_u16_sdwa v19, v10, s3 dst_sel:DWORD dst_unused:UNUSED_PAD src0_sel:WORD_1 src1_sel:DWORD
	v_mul_u32_u24_sdwa v10, v3, s2 dst_sel:DWORD dst_unused:UNUSED_PAD src0_sel:WORD_0 src1_sel:DWORD
	v_mul_lo_u16_sdwa v10, v10, s4 dst_sel:DWORD dst_unused:UNUSED_PAD src0_sel:WORD_1 src1_sel:DWORD
	v_sub_u16_e32 v21, v3, v10
	v_or_b32_e32 v3, 0x240, v1
	v_mul_u32_u24_sdwa v10, v3, s2 dst_sel:DWORD dst_unused:UNUSED_PAD src0_sel:WORD_0 src1_sel:DWORD
	v_lshlrev_b16_e32 v23, 2, v3
	v_or_b32_e32 v3, 0x280, v1
	s_waitcnt lgkmcnt(5)
	v_mul_lo_u16_sdwa v25, v10, s3 dst_sel:DWORD dst_unused:UNUSED_PAD src0_sel:WORD_1 src1_sel:DWORD
	v_mul_u32_u24_sdwa v10, v3, s2 dst_sel:DWORD dst_unused:UNUSED_PAD src0_sel:WORD_0 src1_sel:DWORD
	v_lshlrev_b16_e32 v27, 2, v3
	v_or_b32_e32 v3, 0x2c0, v1
	v_mul_lo_u16_sdwa v29, v10, s3 dst_sel:DWORD dst_unused:UNUSED_PAD src0_sel:WORD_1 src1_sel:DWORD
	v_mul_u32_u24_sdwa v10, v3, s2 dst_sel:DWORD dst_unused:UNUSED_PAD src0_sel:WORD_0 src1_sel:DWORD
	v_or_b32_e32 v12, 0x300, v1
	v_mul_lo_u16_sdwa v8, v8, s3 dst_sel:DWORD dst_unused:UNUSED_PAD src0_sel:WORD_1 src1_sel:DWORD
	v_mul_lo_u16_sdwa v10, v10, s4 dst_sel:DWORD dst_unused:UNUSED_PAD src0_sel:WORD_1 src1_sel:DWORD
	v_mul_u32_u24_sdwa v14, v12, s2 dst_sel:DWORD dst_unused:UNUSED_PAD src0_sel:WORD_0 src1_sel:DWORD
	s_movk_i32 s3, 0x918
	v_or_b32_e32 v16, 0x340, v1
	v_sub_u16_e32 v31, v3, v10
	v_mul_lo_u16_sdwa v10, v14, s3 dst_sel:DWORD dst_unused:UNUSED_PAD src0_sel:WORD_1 src1_sel:DWORD
	v_mul_lo_u16_sdwa v14, v14, s4 dst_sel:DWORD dst_unused:UNUSED_PAD src0_sel:WORD_1 src1_sel:DWORD
	v_mul_u32_u24_sdwa v18, v16, s2 dst_sel:DWORD dst_unused:UNUSED_PAD src0_sel:WORD_0 src1_sel:DWORD
	v_sub_u16_e32 v12, v12, v14
	v_mul_lo_u16_sdwa v14, v18, s3 dst_sel:DWORD dst_unused:UNUSED_PAD src0_sel:WORD_1 src1_sel:DWORD
	v_mul_lo_u16_sdwa v18, v18, s4 dst_sel:DWORD dst_unused:UNUSED_PAD src0_sel:WORD_1 src1_sel:DWORD
	v_sub_u16_e32 v16, v16, v18
	v_or_b32_e32 v18, 0x380, v1
	v_mul_u32_u24_sdwa v20, v18, s2 dst_sel:DWORD dst_unused:UNUSED_PAD src0_sel:WORD_0 src1_sel:DWORD
	v_mul_lo_u16_sdwa v20, v20, s4 dst_sel:DWORD dst_unused:UNUSED_PAD src0_sel:WORD_1 src1_sel:DWORD
	v_sub_u16_e32 v33, v18, v20
	v_or_b32_e32 v18, 0x3c0, v0
	v_mul_u32_u24_sdwa v22, v18, s2 dst_sel:DWORD dst_unused:UNUSED_PAD src0_sel:WORD_0 src1_sel:DWORD
	v_mul_lo_u16_sdwa v20, v22, s3 dst_sel:DWORD dst_unused:UNUSED_PAD src0_sel:WORD_1 src1_sel:DWORD
	v_mul_lo_u16_sdwa v22, v22, s4 dst_sel:DWORD dst_unused:UNUSED_PAD src0_sel:WORD_1 src1_sel:DWORD
	v_sub_u16_e32 v18, v18, v22
	v_lshlrev_b16_e32 v22, 2, v18
	v_or_b32_e32 v18, 0x400, v1
	s_movk_i32 s2, 0xa8f
	v_mul_u32_u24_sdwa v24, v18, s2 dst_sel:DWORD dst_unused:UNUSED_PAD src0_sel:WORD_0 src1_sel:DWORD
	v_lshrrev_b32_e32 v26, 18, v24
	v_mul_lo_u16_e32 v24, 0x918, v26
	v_mul_lo_u16_e32 v26, 0x61, v26
	v_sub_u16_e32 v18, v18, v26
	v_lshlrev_b16_e32 v26, 2, v18
	v_or_b32_e32 v18, 0x440, v1
	v_mul_u32_u24_sdwa v28, v18, s2 dst_sel:DWORD dst_unused:UNUSED_PAD src0_sel:WORD_0 src1_sel:DWORD
	v_lshrrev_b32_e32 v28, 18, v28
	v_mul_lo_u16_e32 v28, 0x61, v28
	v_sub_u16_e32 v35, v18, v28
	v_or_b32_e32 v18, 0x480, v1
	v_mul_u32_u24_sdwa v28, v18, s2 dst_sel:DWORD dst_unused:UNUSED_PAD src0_sel:WORD_0 src1_sel:DWORD
	v_lshrrev_b32_e32 v28, 18, v28
	v_mul_lo_u16_e32 v30, 0x918, v28
	v_mul_lo_u16_e32 v28, 0x61, v28
	v_sub_u16_e32 v18, v18, v28
	v_lshlrev_b16_e32 v32, 2, v18
	v_or_b32_e32 v18, 0x4c0, v1
	v_mul_u32_u24_sdwa v28, v18, s2 dst_sel:DWORD dst_unused:UNUSED_PAD src0_sel:WORD_0 src1_sel:DWORD
	v_lshrrev_b32_e32 v28, 18, v28
	v_mul_lo_u16_e32 v34, 0x918, v28
	v_mul_lo_u16_e32 v28, 0x61, v28
	v_sub_u16_e32 v18, v18, v28
	s_waitcnt lgkmcnt(4)
; #define LAS __attribute__((address_space(3)))
; __device__ __forceinline__ void scan_prompt_wave(const Params& P, unsigned char* lds, int b, int h, int quarter) {
;     ...
;         const float* g0 = (const float*)(P.ws + WS_RSB) + ((size_t)(b * SEQ) * RH + h) * RSB_BLK;
;         LAS unsigned char* l3 = (LAS unsigned char*)lds;
;         int soff[SC_NP64];
; #pragma unroll
;         for (int j = 0; j < SC_NP64; ++j) { const int i = j * 64 + lane; const int ii = i < SC_NPIECE ? i : SC_NPIECE - 1; soff[j] = (ii / 97) * PST + (ii % 97) * 4; }
;         for (int c = 0; c < NCH; ++c) {
	v_lshlrev_b16_e32 v36, 2, v18
	v_or_b32_e32 v18, 0x500, v1
	v_mul_u32_u24_sdwa v28, v18, s2 dst_sel:DWORD dst_unused:UNUSED_PAD src0_sel:WORD_0 src1_sel:DWORD
	v_lshrrev_b32_e32 v28, 18, v28
	v_mul_lo_u16_e32 v28, 0x61, v28
	v_sub_u16_e32 v37, v18, v28
	v_or_b32_e32 v18, 0x540, v1
	v_mul_u32_u24_sdwa v28, v18, s2 dst_sel:DWORD dst_unused:UNUSED_PAD src0_sel:WORD_0 src1_sel:DWORD
	v_lshrrev_b32_e32 v28, 18, v28
	v_mul_lo_u16_e32 v40, 0x918, v28
	v_mul_lo_u16_e32 v28, 0x61, v28
	v_sub_u16_e32 v18, v18, v28
	v_lshlrev_b16_e32 v42, 2, v18
	v_or_b32_e32 v18, 0x580, v1
	v_mul_u32_u24_sdwa v28, v18, s2 dst_sel:DWORD dst_unused:UNUSED_PAD src0_sel:WORD_0 src1_sel:DWORD
	v_lshrrev_b32_e32 v28, 18, v28
	v_mul_lo_u16_e32 v44, 0x918, v28
	v_mul_lo_u16_e32 v28, 0x61, v28
	v_sub_u16_e32 v18, v18, v28
	v_lshlrev_b16_e32 v46, 2, v18
	v_or_b32_e32 v18, 0x5c0, v1
	v_mul_u32_u24_sdwa v28, v18, s2 dst_sel:DWORD dst_unused:UNUSED_PAD src0_sel:WORD_0 src1_sel:DWORD
	v_lshrrev_b32_e32 v28, 18, v28
	v_mul_lo_u16_e32 v28, 0x61, v28
	v_sub_u16_e32 v18, v18, v28
	v_lshlrev_b16_e32 v39, 2, v18
	v_or_b32_e32 v18, 0x600, v1
	v_min_u32_e32 v18, 0x60f, v18
	s_mulk_i32 s33, 0x6000
	v_mul_u32_u24_e32 v28, 0xa8f, v18
	s_or_b32 s0, s33, s40
	v_lshrrev_b32_e32 v28, 18, v28
	s_mulk_i32 s0, 0x610
	v_mul_lo_u16_e32 v28, 0x61, v28
	v_mov_b32_e32 v5, 0x794
	v_lshrrev_b16_e32 v6, 14, v6
	v_sub_u16_e32 v18, v18, v28
	s_add_u32 s0, s78, s0
	v_cndmask_b32_e32 v5, 0, v5, vcc
	v_mul_lo_u16_e32 v6, 0x794, v6
	v_lshlrev_b16_e32 v41, 2, v18
	s_addc_u32 s2, s79, 0
	v_lshlrev_b32_e32 v2, 2, v1
	v_lshlrev_b16_e32 v12, 2, v12
	v_lshlrev_b16_e32 v16, 2, v16
	s_add_u32 s24, s0, 0xa2d4000
	v_add_u16_e32 v4, v5, v4
	v_add_u16_e32 v6, v6, v7
	v_add_u16_e32 v8, v8, v9
	v_lshlrev_b16_e32 v18, 2, v11
	v_add_u16_e32 v28, v15, v13
	v_add_u16_e32 v38, v19, v17
	v_lshlrev_b16_e32 v54, 2, v21
	v_add_u16_e32 v56, v25, v23
	v_add_u16_e32 v58, v29, v27
	s_waitcnt lgkmcnt(1)
	v_lshlrev_b16_e32 v60, 2, v31
	v_lshlrev_b16_e32 v62, 2, v33
	v_lshlrev_b16_e32 v64, 2, v35
	v_lshlrev_b16_e32 v66, 2, v37
	v_add_u16_e32 v68, 0x8868, v39
	v_add_u16_e32 v70, 0x8868, v41
	s_mov_b32 s1, 0
	v_mov_b32_e32 v3, 0
	s_addc_u32 s25, s2, 0
	v_cmp_eq_u32_e64 s[4:5], 0, v1
	v_cmp_gt_u32_e64 s[6:7], 16, v1
	s_add_i32 s26, 0, 0x23004
	s_add_i32 s27, 0, 0x23008
	s_add_i32 s28, 0, 0x2300c
	s_add_i32 s29, 0, 0x23010
	v_lshlrev_b32_e32 v2, 2, v2
	v_lshlrev_b32_e32 v48, 2, v4
	s_mov_b64 s[2:3], 0x2650
	v_lshlrev_b32_e32 v49, 2, v6
	v_lshlrev_b32_e32 v50, 2, v8
	v_lshlrev_b32_e32 v4, 2, v18
	s_mov_b64 s[8:9], 0x6d20
	v_lshlrev_b32_e32 v51, 2, v28
	v_lshlrev_b32_e32 v52, 2, v38
	v_lshlrev_b32_e32 v6, 2, v54
	s_mov_b64 s[10:11], 0xb5e0
	v_lshlrev_b32_e32 v53, 2, v56
	v_lshlrev_b32_e32 v54, 2, v58
	v_lshlrev_b32_e32 v8, 2, v60
	s_mov_b64 s[12:13], 0xfea0
	v_lshlrev_b32_e32 v10, 2, v10
	v_lshlrev_b32_e32 v12, 2, v12
	v_lshlrev_b32_e32 v14, 2, v14
	v_lshlrev_b32_e32 v16, 2, v16
	v_lshlrev_b32_e32 v18, 2, v62
	s_mov_b64 s[14:15], 0x14760
	v_lshlrev_b32_e32 v20, 2, v20
	v_lshlrev_b32_e32 v22, 2, v22
	v_lshlrev_b32_e32 v24, 2, v24
	v_lshlrev_b32_e32 v26, 2, v26
	v_lshlrev_b32_e32 v28, 2, v64
	s_mov_b64 s[16:17], 0x19020
	v_lshlrev_b32_e32 v30, 2, v30
	v_lshlrev_b32_e32 v32, 2, v32
	v_lshlrev_b32_e32 v34, 2, v34
	v_lshlrev_b32_e32 v36, 2, v36
	v_lshlrev_b32_e32 v38, 2, v66
	s_mov_b64 s[18:19], 0x1d8e0
	v_lshlrev_b32_e32 v40, 2, v40
	v_lshlrev_b32_e32 v42, 2, v42
	v_lshlrev_b32_e32 v44, 2, v44
	v_lshlrev_b32_e32 v46, 2, v46
	v_lshlrev_b32_e32 v55, 2, v68
	v_lshlrev_b32_e32 v56, 2, v70
	s_add_i32 s30, 0, 0x23000
	s_mov_b32 s31, 0
	s_branch .LBB0_1238

; __device__ __forceinline__ void scan_prompt_wave(const Params& P, unsigned char* lds, int b, int h, int quarter) {
;     ...
;         asm volatile("s_waitcnt vmcnt(0)" ::: "memory");
;         if (lane == 0) scw[0] = (unsigned)NCH;
;     } else if (wave < 4) {
; __device__ __forceinline__ void p3_scan_and_sb(const Params& P, float* lds) {
;     ...
;         if (wave >= 5 + SC_FREE_WAVES) {
;             constexpr unsigned NCHU = SEQ / SCH;
;             while (scw[1] < NCHU || scw[2] < NCHU || scw[3] < NCHU || scw[4] < NCHU) __builtin_amdgcn_s_sleep(32);
.LBB0_1246:
	s_setprio 0
	s_waitcnt vmcnt(0)
	s_and_saveexec_b64 s[0:1], s[4:5]
	s_add_i32 s2, 0, 0x23000
	v_mov_b32_e32 v2, 0x100
	v_mov_b32_e32 v3, s2
	ds_write_b32 v3, v2
	s_or_b64 exec, exec, s[0:1]
	s_movk_i32 s0, 0x1bf
	v_cmp_lt_u32_e32 vcc, s0, v0
	s_and_saveexec_b64 s[0:1], vcc
	s_cbranch_execz .LBB0_1260
	s_branch .LBB0_1252
